# also NA QK loads 3 pairs ahead; scanB output waves: 4x4 in-quad DPP transpose + 4 dwordx4 stores instead of 16 dword stores
# speedup vs baseline: 1.0499x; 1.0044x over previous
.LBB0_873:
	s_or_b64 exec, exec, s[44:45]
	s_ashr_i32 s12, s12, 12
	s_lshl_b32 s27, s12, 13
	s_lshl_b32 s13, s13, 6
	s_or_b32 s13, s13, s27
	v_or_b32_e32 v148, s13, v162
	v_mov_b64_e32 v[150:151], s[58:59]
	v_mad_i64_i32 v[0:1], s[44:45], v148, s17, v[150:151]
	s_lshl_b32 s24, s83, 7
	s_or_b32 s44, s9, s27
	s_lshl_b32 s11, s11, 6
	v_lshl_add_u64 v[0:1], v[0:1], 0, s[24:25]
	v_lshlrev_b64 v[152:153], 1, v[134:135]
	s_add_i32 s13, s11, 0xffffff00
	v_add_u32_e32 v8, s44, v133
	v_lshl_add_u64 v[0:1], v[0:1], 0, v[152:153]
	v_add_u32_e32 v9, s13, v8
	global_load_dwordx4 v[128:131], v[0:1], off
	global_load_dwordx4 v[12:15], v[0:1], off offset:64
	v_mad_i64_i32 v[0:1], s[46:47], v9, s17, v[150:151]
	v_lshl_add_u64 v[0:1], v[0:1], 0, s[24:25]
	v_lshl_add_u64 v[0:1], v[0:1], 0, v[152:153]
	global_load_dwordx4 v[230:233], v[0:1], off offset:1024
	s_add_i32 s33, s11, 0xffffff40
	global_load_dwordx4 v[234:237], v[0:1], off offset:1088
	s_add_i32 s66, s11, 0xffffff80
	s_sub_i32 s67, s11, 64
	s_or_b32 s44, s44, s11
	s_add_i32 s80, s11, 64
	s_add_i32 s81, s11, 0x80
	s_add_i32 s82, s11, 0xc0
	s_lshl_b32 s27, s12, 8
	v_add_u32_e32 v149, s27, v171
	v_or_b32_e32 v0, 4, v9
	v_mad_i64_i32 v[0:1], s[46:47], v0, s17, v[150:151]
	v_lshl_add_u64 v[0:1], v[0:1], 0, s[24:25]
	v_lshl_add_u64 v[0:1], v[0:1], 0, v[152:153]
	global_load_dwordx4 v[240:243], v[0:1], off offset:1024
	v_add_u32_e32 v9, s33, v8
	global_load_dwordx4 v[244:247], v[0:1], off offset:1088
	v_mad_i64_i32 v[0:1], s[46:47], v9, s17, v[150:151]
	v_lshl_add_u64 v[0:1], v[0:1], 0, s[24:25]
	v_lshl_add_u64 v[0:1], v[0:1], 0, v[152:153]
	global_load_dwordx4 v[248:251], v[0:1], off offset:1024
	global_load_dwordx4 v[4:7], v[0:1], off offset:1088
	s_waitcnt vmcnt(5)
	v_mfma_f32_16x16x32_bf16 v[124:127], v[230:233], v[128:131], 0
	s_waitcnt vmcnt(4)
	v_mfma_f32_16x16x32_bf16 v[124:127], v[234:237], v[12:15], v[124:127]
	v_or_b32_e32 v0, 4, v9
	v_mad_i64_i32 v[0:1], s[46:47], v0, s17, v[150:151]
	v_lshl_add_u64 v[0:1], v[0:1], 0, s[24:25]
	v_lshl_add_u64 v[0:1], v[0:1], 0, v[152:153]
	global_load_dwordx4 v[230:233], v[0:1], off offset:1024
	global_load_dwordx4 v[234:237], v[0:1], off offset:1088
	s_waitcnt vmcnt(5)
	v_mfma_f32_16x16x32_bf16 v[120:123], v[240:243], v[128:131], 0
	s_waitcnt vmcnt(4)
	v_mfma_f32_16x16x32_bf16 v[120:123], v[244:247], v[12:15], v[120:123]
	v_add_u32_e32 v9, s66, v8
	v_mad_i64_i32 v[0:1], s[46:47], v9, s17, v[150:151]
	v_lshl_add_u64 v[0:1], v[0:1], 0, s[24:25]
	v_lshl_add_u64 v[0:1], v[0:1], 0, v[152:153]
	global_load_dwordx4 v[240:243], v[0:1], off offset:1024
	global_load_dwordx4 v[244:247], v[0:1], off offset:1088
	s_waitcnt vmcnt(5)
	v_mfma_f32_16x16x32_bf16 v[116:119], v[248:251], v[128:131], 0
	s_waitcnt vmcnt(4)
	v_mfma_f32_16x16x32_bf16 v[116:119], v[4:7], v[12:15], v[116:119]
	v_or_b32_e32 v0, 4, v9
	v_mad_i64_i32 v[0:1], s[46:47], v0, s17, v[150:151]
	v_lshl_add_u64 v[0:1], v[0:1], 0, s[24:25]
	v_lshl_add_u64 v[0:1], v[0:1], 0, v[152:153]
	global_load_dwordx4 v[248:251], v[0:1], off offset:1024
	global_load_dwordx4 v[4:7], v[0:1], off offset:1088
	s_waitcnt vmcnt(5)
	v_mfma_f32_16x16x32_bf16 v[104:107], v[230:233], v[128:131], 0
	s_waitcnt vmcnt(4)
	v_mfma_f32_16x16x32_bf16 v[104:107], v[234:237], v[12:15], v[104:107]
	v_add_u32_e32 v9, s67, v8
	v_mad_i64_i32 v[0:1], s[46:47], v9, s17, v[150:151]
	v_lshl_add_u64 v[0:1], v[0:1], 0, s[24:25]
	v_lshl_add_u64 v[0:1], v[0:1], 0, v[152:153]
	global_load_dwordx4 v[230:233], v[0:1], off offset:1024
	global_load_dwordx4 v[234:237], v[0:1], off offset:1088
	s_waitcnt vmcnt(5)
	v_mfma_f32_16x16x32_bf16 v[100:103], v[240:243], v[128:131], 0
	s_waitcnt vmcnt(4)
	v_mfma_f32_16x16x32_bf16 v[100:103], v[244:247], v[12:15], v[100:103]
	v_or_b32_e32 v0, 4, v9
	v_mad_i64_i32 v[0:1], s[46:47], v0, s17, v[150:151]
	v_lshl_add_u64 v[0:1], v[0:1], 0, s[24:25]
	v_lshl_add_u64 v[0:1], v[0:1], 0, v[152:153]
	global_load_dwordx4 v[240:243], v[0:1], off offset:1024
	global_load_dwordx4 v[244:247], v[0:1], off offset:1088
	s_waitcnt vmcnt(5)
	v_mfma_f32_16x16x32_bf16 v[88:91], v[248:251], v[128:131], 0
	s_waitcnt vmcnt(4)
	v_mfma_f32_16x16x32_bf16 v[88:91], v[4:7], v[12:15], v[88:91]
	v_add_u32_e32 v9, s44, v133
	v_mad_i64_i32 v[0:1], s[44:45], v9, s17, v[150:151]
	v_lshl_add_u64 v[0:1], v[0:1], 0, s[24:25]
	v_lshl_add_u64 v[0:1], v[0:1], 0, v[152:153]
	global_load_dwordx4 v[248:251], v[0:1], off offset:1024
	global_load_dwordx4 v[4:7], v[0:1], off offset:1088
	s_waitcnt vmcnt(5)
	v_mfma_f32_16x16x32_bf16 v[92:95], v[230:233], v[128:131], 0
	s_waitcnt vmcnt(4)
	v_mfma_f32_16x16x32_bf16 v[92:95], v[234:237], v[12:15], v[92:95]
	v_or_b32_e32 v0, 4, v9
	v_mad_i64_i32 v[0:1], s[44:45], v0, s17, v[150:151]
	v_lshl_add_u64 v[0:1], v[0:1], 0, s[24:25]
	v_lshl_add_u64 v[0:1], v[0:1], 0, v[152:153]
	global_load_dwordx4 v[230:233], v[0:1], off offset:1024
	global_load_dwordx4 v[234:237], v[0:1], off offset:1088
	s_waitcnt vmcnt(5)
	v_mfma_f32_16x16x32_bf16 v[112:115], v[240:243], v[128:131], 0
	s_waitcnt vmcnt(4)
	v_mfma_f32_16x16x32_bf16 v[112:115], v[244:247], v[12:15], v[112:115]
	v_add_u32_e32 v9, s80, v8
	v_mad_i64_i32 v[0:1], s[44:45], v9, s17, v[150:151]
	v_lshl_add_u64 v[0:1], v[0:1], 0, s[24:25]
	v_lshl_add_u64 v[0:1], v[0:1], 0, v[152:153]
	global_load_dwordx4 v[240:243], v[0:1], off offset:1024
	global_load_dwordx4 v[244:247], v[0:1], off offset:1088
	s_waitcnt vmcnt(5)
	v_mfma_f32_16x16x32_bf16 v[108:111], v[248:251], v[128:131], 0
	s_waitcnt vmcnt(4)
	v_mfma_f32_16x16x32_bf16 v[108:111], v[4:7], v[12:15], v[108:111]
	v_or_b32_e32 v0, 4, v9
	v_mad_i64_i32 v[0:1], s[44:45], v0, s17, v[150:151]
	v_lshl_add_u64 v[0:1], v[0:1], 0, s[24:25]
	v_lshl_add_u64 v[0:1], v[0:1], 0, v[152:153]
	global_load_dwordx4 v[248:251], v[0:1], off offset:1024
	global_load_dwordx4 v[4:7], v[0:1], off offset:1088
	s_waitcnt vmcnt(5)
	v_mfma_f32_16x16x32_bf16 v[96:99], v[230:233], v[128:131], 0
	s_waitcnt vmcnt(4)
	v_mfma_f32_16x16x32_bf16 v[96:99], v[234:237], v[12:15], v[96:99]
	v_add_u32_e32 v9, s81, v8
	v_add_u32_e32 v8, s82, v8
	v_mad_i64_i32 v[0:1], s[44:45], v9, s17, v[150:151]
	v_lshl_add_u64 v[0:1], v[0:1], 0, s[24:25]
	v_lshl_add_u64 v[0:1], v[0:1], 0, v[152:153]
	global_load_dwordx4 v[230:233], v[0:1], off offset:1024
	global_load_dwordx4 v[234:237], v[0:1], off offset:1088
	s_waitcnt vmcnt(5)
	v_mfma_f32_16x16x32_bf16 v[84:87], v[240:243], v[128:131], 0
	s_waitcnt vmcnt(4)
	v_mfma_f32_16x16x32_bf16 v[84:87], v[244:247], v[12:15], v[84:87]
	v_or_b32_e32 v0, 4, v9
	v_mad_i64_i32 v[0:1], s[44:45], v0, s17, v[150:151]
	v_lshl_add_u64 v[0:1], v[0:1], 0, s[24:25]
	v_lshl_add_u64 v[0:1], v[0:1], 0, v[152:153]
	global_load_dwordx4 v[240:243], v[0:1], off offset:1024
	global_load_dwordx4 v[244:247], v[0:1], off offset:1088
	s_waitcnt vmcnt(5)
	v_mfma_f32_16x16x32_bf16 v[80:83], v[248:251], v[128:131], 0
	s_waitcnt vmcnt(4)
	v_mfma_f32_16x16x32_bf16 v[80:83], v[4:7], v[12:15], v[80:83]
	v_mad_i64_i32 v[0:1], s[44:45], v8, s17, v[150:151]
	v_lshl_add_u64 v[0:1], v[0:1], 0, s[24:25]
	v_lshl_add_u64 v[0:1], v[0:1], 0, v[152:153]
	global_load_dwordx4 v[248:251], v[0:1], off offset:1024
	global_load_dwordx4 v[4:7], v[0:1], off offset:1088
	s_waitcnt vmcnt(5)
	v_mfma_f32_16x16x32_bf16 v[76:79], v[230:233], v[128:131], 0
	s_waitcnt vmcnt(4)
	v_mfma_f32_16x16x32_bf16 v[76:79], v[234:237], v[12:15], v[76:79]
	v_or_b32_e32 v0, 4, v8
	v_mad_i64_i32 v[0:1], s[44:45], v0, s17, v[150:151]
	v_lshl_add_u64 v[0:1], v[0:1], 0, s[24:25]
	v_lshl_add_u64 v[0:1], v[0:1], 0, v[152:153]
	global_load_dwordx4 v[230:233], v[0:1], off offset:1024
	global_load_dwordx4 v[234:237], v[0:1], off offset:1088
	s_waitcnt vmcnt(5)
	v_mfma_f32_16x16x32_bf16 v[72:75], v[240:243], v[128:131], 0
	s_waitcnt vmcnt(4)
	v_mfma_f32_16x16x32_bf16 v[72:75], v[244:247], v[12:15], v[72:75]
	v_add_u32_e32 v8, s27, v164
	v_mad_i64_i32 v[0:1], s[44:45], v8, s17, v[150:151]
	v_lshl_add_u64 v[0:1], v[0:1], 0, s[24:25]
	v_lshl_add_u64 v[0:1], v[0:1], 0, v[152:153]
	global_load_dwordx4 v[240:243], v[0:1], off offset:1024
	global_load_dwordx4 v[244:247], v[0:1], off offset:1088
	s_waitcnt vmcnt(5)
	v_mfma_f32_16x16x32_bf16 v[68:71], v[248:251], v[128:131], 0
	s_waitcnt vmcnt(4)
	v_mfma_f32_16x16x32_bf16 v[68:71], v[4:7], v[12:15], v[68:71]
	v_or_b32_e32 v0, 4, v8
	v_mad_i64_i32 v[0:1], s[44:45], v0, s17, v[150:151]
	v_lshl_add_u64 v[0:1], v[0:1], 0, s[24:25]
	v_lshl_add_u64 v[0:1], v[0:1], 0, v[152:153]
	global_load_dwordx4 v[248:251], v[0:1], off offset:1024
	global_load_dwordx4 v[4:7], v[0:1], off offset:1088
	s_waitcnt vmcnt(5)
	v_mfma_f32_16x16x32_bf16 v[64:67], v[230:233], v[128:131], 0
	s_waitcnt vmcnt(4)
	v_mfma_f32_16x16x32_bf16 v[64:67], v[234:237], v[12:15], v[64:67]
	v_add_u32_e32 v8, s27, v165
	v_mad_i64_i32 v[0:1], s[44:45], v8, s17, v[150:151]
	v_lshl_add_u64 v[0:1], v[0:1], 0, s[24:25]
	v_lshl_add_u64 v[0:1], v[0:1], 0, v[152:153]
	global_load_dwordx4 v[230:233], v[0:1], off offset:1024
	global_load_dwordx4 v[234:237], v[0:1], off offset:1088
	s_waitcnt vmcnt(5)
	v_mfma_f32_16x16x32_bf16 v[48:51], v[240:243], v[128:131], 0
	s_waitcnt vmcnt(4)
	v_mfma_f32_16x16x32_bf16 v[48:51], v[244:247], v[12:15], v[48:51]
	v_or_b32_e32 v0, 4, v8
	v_mad_i64_i32 v[0:1], s[44:45], v0, s17, v[150:151]
	v_lshl_add_u64 v[0:1], v[0:1], 0, s[24:25]
	v_lshl_add_u64 v[0:1], v[0:1], 0, v[152:153]
	global_load_dwordx4 v[240:243], v[0:1], off offset:1024
	global_load_dwordx4 v[244:247], v[0:1], off offset:1088
	s_waitcnt vmcnt(5)
	v_mfma_f32_16x16x32_bf16 v[56:59], v[248:251], v[128:131], 0
	s_waitcnt vmcnt(4)
	v_mfma_f32_16x16x32_bf16 v[56:59], v[4:7], v[12:15], v[56:59]
	v_add_u32_e32 v8, s27, v166
	v_mad_i64_i32 v[0:1], s[44:45], v8, s17, v[150:151]
	v_lshl_add_u64 v[0:1], v[0:1], 0, s[24:25]
	v_lshl_add_u64 v[0:1], v[0:1], 0, v[152:153]
	global_load_dwordx4 v[248:251], v[0:1], off offset:1024
	global_load_dwordx4 v[4:7], v[0:1], off offset:1088
	s_waitcnt vmcnt(5)
	v_mfma_f32_16x16x32_bf16 v[52:55], v[230:233], v[128:131], 0
	s_waitcnt vmcnt(4)
	v_mfma_f32_16x16x32_bf16 v[52:55], v[234:237], v[12:15], v[52:55]
	v_or_b32_e32 v0, 4, v8
	v_mad_i64_i32 v[0:1], s[44:45], v0, s17, v[150:151]
	v_lshl_add_u64 v[0:1], v[0:1], 0, s[24:25]
	v_lshl_add_u64 v[0:1], v[0:1], 0, v[152:153]
	global_load_dwordx4 v[230:233], v[0:1], off offset:1024
	global_load_dwordx4 v[234:237], v[0:1], off offset:1088
	s_waitcnt vmcnt(5)
	v_mfma_f32_16x16x32_bf16 v[60:63], v[240:243], v[128:131], 0
	s_waitcnt vmcnt(4)
	v_mfma_f32_16x16x32_bf16 v[60:63], v[244:247], v[12:15], v[60:63]
	v_add_u32_e32 v8, s27, v167
	v_mad_i64_i32 v[0:1], s[44:45], v8, s17, v[150:151]
	v_lshl_add_u64 v[0:1], v[0:1], 0, s[24:25]
	v_lshl_add_u64 v[0:1], v[0:1], 0, v[152:153]
	global_load_dwordx4 v[240:243], v[0:1], off offset:1024
	global_load_dwordx4 v[244:247], v[0:1], off offset:1088
	s_waitcnt vmcnt(5)
	v_mfma_f32_16x16x32_bf16 v[32:35], v[248:251], v[128:131], 0
	s_waitcnt vmcnt(4)
	v_mfma_f32_16x16x32_bf16 v[32:35], v[4:7], v[12:15], v[32:35]
	v_or_b32_e32 v0, 4, v8
	v_mad_i64_i32 v[0:1], s[44:45], v0, s17, v[150:151]
	v_lshl_add_u64 v[0:1], v[0:1], 0, s[24:25]
	v_lshl_add_u64 v[0:1], v[0:1], 0, v[152:153]
	global_load_dwordx4 v[248:251], v[0:1], off offset:1024
	global_load_dwordx4 v[4:7], v[0:1], off offset:1088
	s_waitcnt vmcnt(5)
	v_mfma_f32_16x16x32_bf16 v[40:43], v[230:233], v[128:131], 0
	s_waitcnt vmcnt(4)
	v_mfma_f32_16x16x32_bf16 v[40:43], v[234:237], v[12:15], v[40:43]
	v_add_u32_e32 v8, s27, v168
	v_mad_i64_i32 v[0:1], s[44:45], v8, s17, v[150:151]
	v_lshl_add_u64 v[0:1], v[0:1], 0, s[24:25]
	v_lshl_add_u64 v[0:1], v[0:1], 0, v[152:153]
	global_load_dwordx4 v[230:233], v[0:1], off offset:1024
	global_load_dwordx4 v[234:237], v[0:1], off offset:1088
	s_waitcnt vmcnt(5)
	v_mfma_f32_16x16x32_bf16 v[36:39], v[240:243], v[128:131], 0
	s_waitcnt vmcnt(4)
	v_mfma_f32_16x16x32_bf16 v[36:39], v[244:247], v[12:15], v[36:39]
	v_or_b32_e32 v0, 4, v8
	v_mad_i64_i32 v[0:1], s[44:45], v0, s17, v[150:151]
	v_lshl_add_u64 v[0:1], v[0:1], 0, s[24:25]
	v_lshl_add_u64 v[0:1], v[0:1], 0, v[152:153]
	global_load_dwordx4 v[240:243], v[0:1], off offset:1024
	global_load_dwordx4 v[244:247], v[0:1], off offset:1088
	s_waitcnt vmcnt(5)
	v_mfma_f32_16x16x32_bf16 v[44:47], v[248:251], v[128:131], 0
	s_waitcnt vmcnt(4)
	v_mfma_f32_16x16x32_bf16 v[44:47], v[4:7], v[12:15], v[44:47]
	v_add_u32_e32 v8, s27, v169
	v_mad_i64_i32 v[0:1], s[44:45], v8, s17, v[150:151]
	v_lshl_add_u64 v[0:1], v[0:1], 0, s[24:25]
	v_lshl_add_u64 v[0:1], v[0:1], 0, v[152:153]
	global_load_dwordx4 v[248:251], v[0:1], off offset:1024
	global_load_dwordx4 v[4:7], v[0:1], off offset:1088
	s_waitcnt vmcnt(5)
	v_mfma_f32_16x16x32_bf16 v[28:31], v[230:233], v[128:131], 0
	s_waitcnt vmcnt(4)
	v_mfma_f32_16x16x32_bf16 v[28:31], v[234:237], v[12:15], v[28:31]
	v_or_b32_e32 v0, 4, v8
	v_mad_i64_i32 v[0:1], s[44:45], v0, s17, v[150:151]
	v_lshl_add_u64 v[0:1], v[0:1], 0, s[24:25]
	v_lshl_add_u64 v[0:1], v[0:1], 0, v[152:153]
	global_load_dwordx4 v[230:233], v[0:1], off offset:1024
	global_load_dwordx4 v[234:237], v[0:1], off offset:1088
	s_waitcnt vmcnt(5)
	v_mfma_f32_16x16x32_bf16 v[24:27], v[240:243], v[128:131], 0
	s_waitcnt vmcnt(4)
	v_mfma_f32_16x16x32_bf16 v[24:27], v[244:247], v[12:15], v[24:27]
	s_waitcnt vmcnt(3)
	v_mfma_f32_16x16x32_bf16 v[20:23], v[248:251], v[128:131], 0
	s_waitcnt vmcnt(2)
	v_mfma_f32_16x16x32_bf16 v[20:23], v[4:7], v[12:15], v[20:23]
	s_waitcnt vmcnt(1)
	v_mfma_f32_16x16x32_bf16 v[16:19], v[230:233], v[128:131], 0
	s_waitcnt vmcnt(0)
	v_mfma_f32_16x16x32_bf16 v[16:19], v[234:237], v[12:15], v[16:19]
	v_add_u32_e32 v8, s27, v170
	s_nop 3
	v_mad_i64_i32 v[0:1], s[44:45], v8, s17, v[150:151]
	v_lshl_add_u64 v[0:1], v[0:1], 0, s[24:25]
	v_lshl_add_u64 v[4:5], v[0:1], 0, v[152:153]
	global_load_dwordx4 v[0:3], v[4:5], off offset:1024
	s_waitcnt vmcnt(0)
	v_mfma_f32_16x16x32_bf16 v[0:3], v[0:3], v[128:131], 0
	global_load_dwordx4 v[4:7], v[4:5], off offset:1088
	s_waitcnt vmcnt(0)
	v_mfma_f32_16x16x32_bf16 v[0:3], v[4:7], v[12:15], v[0:3]
	v_or_b32_e32 v4, 4, v8
	v_mad_i64_i32 v[4:5], s[44:45], v4, s17, v[150:151]
	v_lshl_add_u64 v[4:5], v[4:5], 0, s[24:25]
	v_lshl_add_u64 v[8:9], v[4:5], 0, v[152:153]
	global_load_dwordx4 v[4:7], v[8:9], off offset:1024
	s_waitcnt vmcnt(0)
	v_mfma_f32_16x16x32_bf16 v[4:7], v[4:7], v[128:131], 0
	global_load_dwordx4 v[8:11], v[8:9], off offset:1088
	s_waitcnt vmcnt(0)
	v_mfma_f32_16x16x32_bf16 v[8:11], v[8:11], v[12:15], v[4:7]
	s_nop 4
	v_mad_i64_i32 v[4:5], s[44:45], v149, s17, v[150:151]
	v_lshl_add_u64 v[4:5], v[4:5], 0, s[24:25]
	v_lshl_add_u64 v[172:173], v[4:5], 0, v[152:153]
	global_load_dwordx4 v[4:7], v[172:173], off offset:1024
	s_waitcnt vmcnt(0)
	v_mfma_f32_16x16x32_bf16 v[4:7], v[4:7], v[128:131], 0
	global_load_dwordx4 v[172:175], v[172:173], off offset:1088
	v_or_b32_e32 v149, 4, v149
	v_mad_i64_i32 v[150:151], s[44:45], v149, s17, v[150:151]
	v_lshl_add_u64 v[150:151], v[150:151], 0, s[24:25]
	s_waitcnt vmcnt(0)
	v_mfma_f32_16x16x32_bf16 v[4:7], v[172:175], v[12:15], v[4:7]
	v_lshl_add_u64 v[172:173], v[150:151], 0, v[152:153]
	global_load_dwordx4 v[150:153], v[172:173], off offset:1024
	s_waitcnt vmcnt(0)
	v_mfma_f32_16x16x32_bf16 v[128:131], v[150:153], v[128:131], 0
	global_load_dwordx4 v[150:153], v[172:173], off offset:1088
	s_waitcnt lgkmcnt(0)
	s_waitcnt vmcnt(0)
	v_mfma_f32_16x16x32_bf16 v[12:15], v[150:153], v[12:15], v[128:131]
	v_add_u32_e32 v151, s9, v134
	s_nop 3
	v_sub_u32_e32 v128, v151, v163
	v_add_u32_e32 v128, 8, v128
	v_sub_u32_e32 v129, v151, v162
	v_cmp_gt_u32_e32 vcc, 16, v128
	v_mov_b32_e32 v128, 0xf149f2ca
	v_med3_i32 v130, v129, -15, 15
	v_mov_b32_e32 v129, 0xf149f2ca
	s_and_saveexec_b64 s[44:45], vcc
	s_cbranch_execz .LBB0_875
	v_lshl_add_u32 v129, v130, 2, s2
	ds_read_b32 v129, v129 offset:60
	s_waitcnt lgkmcnt(0)
	v_fmac_f32_e32 v129, 0x3e38aa3b, v124

.LBB0_1154:
	s_mov_b64 s[36:37], -1
	s_and_b64 vcc, exec, s[38:39]
	s_cbranch_vccz .LBB0_1168
	s_and_b64 vcc, exec, s[40:41]
	s_cbranch_vccz .LBB0_1163
	s_bfe_u32 s27, s10, 0x10004
	s_ashr_i32 s12, s10, 5
	s_mul_i32 s11, s27, 0x4200000
	s_add_u32 s11, s5, s11
	s_addc_u32 s13, s6, 0
	s_lshl_b32 s24, s10, 8
	s_and_b32 s24, s24, 0xf00
	s_add_u32 s44, s11, s24
	s_addc_u32 s45, s13, 0
	s_lshl_b32 s11, s12, 13
	s_lshl_b32 s12, s12, 8
	s_addk_i32 s12, 0x4000
	s_lshl_b32 s13, s27, 2
	s_cmp_eq_u32 s27, 0
	s_cselect_b64 s[36:37], -1, 0
	s_waitcnt vmcnt(41)
	v_cndmask_b32_e64 v0, v197, v196, s[36:37]
	v_lshl_add_u32 v208, v0, 12, v200
	s_waitcnt lgkmcnt(0)
	s_barrier
	s_waitcnt lgkmcnt(0)
	s_waitcnt vmcnt(37)
	v_lshl_add_u64 v[16:17], v[208:209], 2, s[44:45]
	s_and_b64 s[44:45], s[36:37], exec
	s_mov_b32 s24, 0
	s_cselect_b32 s27, 1, -1
	s_cselect_b32 s33, 2, -2
	s_cselect_b32 s43, 3, -3
	s_cselect_b32 s46, 8, -8
	s_cselect_b32 s47, 9, -9
	s_cselect_b32 s48, 10, -10
	s_cselect_b32 s49, 11, -11
	s_cselect_b32 s50, 16, -16
	s_cselect_b32 s51, 17, 0xffffffef
	s_cselect_b32 s52, 18, 0xffffffee
	s_cselect_b32 s53, 19, 0xffffffed
	s_cselect_b32 s54, 24, 0xffffffe8
	s_cselect_b32 s55, 25, 0xffffffe7
	s_cselect_b32 s56, 26, 0xffffffe6
	s_cselect_b32 s57, 27, 0xffffffe5
	s_movk_i32 s58, 0x20ff
	s_mov_b32 s59, 0
	s_mov_b32 s60, 0
	s_mov_b32 s61, 0
	v_mbcnt_lo_u32_b32 v210, -1, 0
	v_mbcnt_hi_u32_b32 v210, -1, v210
	v_and_b32_e32 v210, 3, v210
	s_lshl_b32 s62, s27, 12
	s_add_i32 s62, s62, -4
	v_mul_lo_u32 v210, v210, s62
	v_ashrrev_i32_e32 v211, 31, v210
	v_lshl_add_u64 v[216:217], v[16:17], 0, v[210:211]
	s_mov_b32 s100, 0xcccccccc
	s_mov_b32 s101, 0xcccccccc
	s_barrier
	s_waitcnt vmcnt(0)
	s_branch .LBB0_1158
.LBB0_1157:
	s_add_i32 s45, s61, 1
	s_cmp_lg_u32 s61, 2
	s_cselect_b32 s61, s45, 0
	s_sub_i32 s44, s44, s13
	s_add_i32 s44, s44, s62
	s_mov_b32 vcc_lo, 0xaaaaaaaa
	s_mov_b32 vcc_hi, 0xaaaaaaaa
	s_nop 7
	v_mov_b32_dpp v210, v0 quad_perm:[1,0,3,2] row_mask:0xf bank_mask:0xf
	v_mov_b32_dpp v211, v1 quad_perm:[1,0,3,2] row_mask:0xf bank_mask:0xf
	v_cndmask_b32_e32 v0, v0, v211, vcc
	v_cndmask_b32_e32 v1, v210, v1, vcc
	v_mov_b32_dpp v212, v2 quad_perm:[1,0,3,2] row_mask:0xf bank_mask:0xf
	v_mov_b32_dpp v213, v3 quad_perm:[1,0,3,2] row_mask:0xf bank_mask:0xf
	v_cndmask_b32_e32 v2, v2, v213, vcc
	v_cndmask_b32_e32 v3, v212, v3, vcc
	v_mov_b32_dpp v210, v4 quad_perm:[1,0,3,2] row_mask:0xf bank_mask:0xf
	v_mov_b32_dpp v211, v5 quad_perm:[1,0,3,2] row_mask:0xf bank_mask:0xf
	v_cndmask_b32_e32 v4, v4, v211, vcc
	v_cndmask_b32_e32 v5, v210, v5, vcc
	v_mov_b32_dpp v212, v6 quad_perm:[1,0,3,2] row_mask:0xf bank_mask:0xf
	v_mov_b32_dpp v213, v7 quad_perm:[1,0,3,2] row_mask:0xf bank_mask:0xf
	v_cndmask_b32_e32 v6, v6, v213, vcc
	v_cndmask_b32_e32 v7, v212, v7, vcc
	v_mov_b32_dpp v210, v8 quad_perm:[1,0,3,2] row_mask:0xf bank_mask:0xf
	v_mov_b32_dpp v211, v9 quad_perm:[1,0,3,2] row_mask:0xf bank_mask:0xf
	v_cndmask_b32_e32 v8, v8, v211, vcc
	v_cndmask_b32_e32 v9, v210, v9, vcc
	v_mov_b32_dpp v212, v10 quad_perm:[1,0,3,2] row_mask:0xf bank_mask:0xf
	v_mov_b32_dpp v213, v11 quad_perm:[1,0,3,2] row_mask:0xf bank_mask:0xf
	v_cndmask_b32_e32 v10, v10, v213, vcc
	v_cndmask_b32_e32 v11, v212, v11, vcc
	v_mov_b32_dpp v210, v12 quad_perm:[1,0,3,2] row_mask:0xf bank_mask:0xf
	v_mov_b32_dpp v211, v13 quad_perm:[1,0,3,2] row_mask:0xf bank_mask:0xf
	v_cndmask_b32_e32 v12, v12, v211, vcc
	v_cndmask_b32_e32 v13, v210, v13, vcc
	v_mov_b32_dpp v212, v14 quad_perm:[1,0,3,2] row_mask:0xf bank_mask:0xf
	v_mov_b32_dpp v213, v15 quad_perm:[1,0,3,2] row_mask:0xf bank_mask:0xf
	v_cndmask_b32_e32 v14, v14, v213, vcc
	v_cndmask_b32_e32 v15, v212, v15, vcc
	v_mov_b32_dpp v210, v0 quad_perm:[2,3,0,1] row_mask:0xf bank_mask:0xf
	v_mov_b32_dpp v211, v2 quad_perm:[2,3,0,1] row_mask:0xf bank_mask:0xf
	v_cndmask_b32_e64 v0, v0, v211, s[100:101]
	v_cndmask_b32_e64 v2, v210, v2, s[100:101]
	v_mov_b32_dpp v212, v1 quad_perm:[2,3,0,1] row_mask:0xf bank_mask:0xf
	v_mov_b32_dpp v213, v3 quad_perm:[2,3,0,1] row_mask:0xf bank_mask:0xf
	v_cndmask_b32_e64 v1, v1, v213, s[100:101]
	v_cndmask_b32_e64 v3, v212, v3, s[100:101]
	v_mov_b32_dpp v210, v4 quad_perm:[2,3,0,1] row_mask:0xf bank_mask:0xf
	v_mov_b32_dpp v211, v6 quad_perm:[2,3,0,1] row_mask:0xf bank_mask:0xf
	v_cndmask_b32_e64 v4, v4, v211, s[100:101]
	v_cndmask_b32_e64 v6, v210, v6, s[100:101]
	v_mov_b32_dpp v212, v5 quad_perm:[2,3,0,1] row_mask:0xf bank_mask:0xf
	v_mov_b32_dpp v213, v7 quad_perm:[2,3,0,1] row_mask:0xf bank_mask:0xf
	v_cndmask_b32_e64 v5, v5, v213, s[100:101]
	v_cndmask_b32_e64 v7, v212, v7, s[100:101]
	v_mov_b32_dpp v210, v8 quad_perm:[2,3,0,1] row_mask:0xf bank_mask:0xf
	v_mov_b32_dpp v211, v10 quad_perm:[2,3,0,1] row_mask:0xf bank_mask:0xf
	v_cndmask_b32_e64 v8, v8, v211, s[100:101]
	v_cndmask_b32_e64 v10, v210, v10, s[100:101]
	v_mov_b32_dpp v212, v9 quad_perm:[2,3,0,1] row_mask:0xf bank_mask:0xf
	v_mov_b32_dpp v213, v11 quad_perm:[2,3,0,1] row_mask:0xf bank_mask:0xf
	v_cndmask_b32_e64 v9, v9, v213, s[100:101]
	v_cndmask_b32_e64 v11, v212, v11, s[100:101]
	v_mov_b32_dpp v210, v12 quad_perm:[2,3,0,1] row_mask:0xf bank_mask:0xf
	v_mov_b32_dpp v211, v14 quad_perm:[2,3,0,1] row_mask:0xf bank_mask:0xf
	v_cndmask_b32_e64 v12, v12, v211, s[100:101]
	v_cndmask_b32_e64 v14, v210, v14, s[100:101]
	v_mov_b32_dpp v212, v13 quad_perm:[2,3,0,1] row_mask:0xf bank_mask:0xf
	v_mov_b32_dpp v213, v15 quad_perm:[2,3,0,1] row_mask:0xf bank_mask:0xf
	v_cndmask_b32_e64 v13, v13, v213, s[100:101]
	v_cndmask_b32_e64 v15, v212, v15, s[100:101]
	s_mov_b32 s62, s44
	s_ashr_i32 s63, s62, 31
	s_lshl_b64 s[62:63], s[62:63], 12
	v_lshl_add_u64 v[214:215], v[216:217], 0, s[62:63]
	global_store_dwordx4 v[214:215], v[0:3], off
	s_add_i32 s62, s44, s46
	s_ashr_i32 s63, s62, 31
	s_lshl_b64 s[62:63], s[62:63], 12
	v_lshl_add_u64 v[214:215], v[216:217], 0, s[62:63]
	global_store_dwordx4 v[214:215], v[4:7], off
	s_add_i32 s62, s44, s50
	s_ashr_i32 s63, s62, 31
	s_lshl_b64 s[62:63], s[62:63], 12
	v_lshl_add_u64 v[214:215], v[216:217], 0, s[62:63]
	global_store_dwordx4 v[214:215], v[8:11], off
	s_add_i32 s62, s44, s54
	s_ashr_i32 s63, s62, 31
	s_lshl_b64 s[62:63], s[62:63], 12
	v_lshl_add_u64 v[214:215], v[216:217], 0, s[62:63]
	global_store_dwordx4 v[214:215], v[12:15], off
	s_waitcnt lgkmcnt(0)
	s_add_i32 s60, s60, 1
	s_sub_i32 s58, s58, 32
	s_add_i32 s59, s59, 32
	s_add_i32 s24, s24, 2
	s_cmp_lg_u32 s58, -1
	s_barrier
	s_cbranch_scc0 .LBB0_1162

	.amdhsa_kernel _Z3fwd4Args
		.amdhsa_group_segment_fixed_size 0
		.amdhsa_private_segment_fixed_size 0
		.amdhsa_kernarg_size 552
		.amdhsa_user_sgpr_count 2
		.amdhsa_user_sgpr_dispatch_ptr 0
		.amdhsa_user_sgpr_queue_ptr 0
		.amdhsa_user_sgpr_kernarg_segment_ptr 1
		.amdhsa_user_sgpr_dispatch_id 0
		.amdhsa_user_sgpr_kernarg_preload_length 0
		.amdhsa_user_sgpr_kernarg_preload_offset 0
		.amdhsa_user_sgpr_private_segment_size 0
		.amdhsa_uses_dynamic_stack 0
		.amdhsa_enable_private_segment 0
		.amdhsa_system_sgpr_workgroup_id_x 1
		.amdhsa_system_sgpr_workgroup_id_y 0
		.amdhsa_system_sgpr_workgroup_id_z 0
		.amdhsa_system_sgpr_workgroup_info 0
		.amdhsa_system_vgpr_workitem_id 0
		.amdhsa_next_free_vgpr 256
		.amdhsa_next_free_sgpr 102
		.amdhsa_accum_offset 256
		.amdhsa_reserve_vcc 1
		.amdhsa_float_round_mode_32 0
		.amdhsa_float_round_mode_16_64 0
		.amdhsa_float_denorm_mode_32 3
		.amdhsa_float_denorm_mode_16_64 3
		.amdhsa_dx10_clamp 1
		.amdhsa_ieee_mode 1
		.amdhsa_fp16_overflow 0
		.amdhsa_tg_split 0
		.amdhsa_exception_fp_ieee_invalid_op 0
		.amdhsa_exception_fp_denorm_src 0
		.amdhsa_exception_fp_ieee_div_zero 0
		.amdhsa_exception_fp_ieee_overflow 0
		.amdhsa_exception_fp_ieee_underflow 0
		.amdhsa_exception_fp_ieee_inexact 0
		.amdhsa_exception_int_div_zero 0
	.end_amdhsa_kernel

amdhsa.kernels:
  - .agpr_count:     0
    .args:
      - .offset:         0
        .size:           296
        .value_kind:     by_value
      - .offset:         296
        .size:           4
        .value_kind:     hidden_block_count_x
      - .offset:         300
        .size:           4
        .value_kind:     hidden_block_count_y
      - .offset:         304
        .size:           4
        .value_kind:     hidden_block_count_z
      - .offset:         308
        .size:           2
        .value_kind:     hidden_group_size_x
      - .offset:         310
        .size:           2
        .value_kind:     hidden_group_size_y
      - .offset:         312
        .size:           2
        .value_kind:     hidden_group_size_z
      - .offset:         314
        .size:           2
        .value_kind:     hidden_remainder_x
      - .offset:         316
        .size:           2
        .value_kind:     hidden_remainder_y
      - .offset:         318
        .size:           2
        .value_kind:     hidden_remainder_z
      - .offset:         336
        .size:           8
        .value_kind:     hidden_global_offset_x
      - .offset:         344
        .size:           8
        .value_kind:     hidden_global_offset_y
      - .offset:         352
        .size:           8
        .value_kind:     hidden_global_offset_z
      - .offset:         360
        .size:           2
        .value_kind:     hidden_grid_dims
      - .offset:         416
        .size:           4
        .value_kind:     hidden_dynamic_lds_size
    .group_segment_fixed_size: 0
    .kernarg_segment_align: 8
    .kernarg_segment_size: 552
    .language:       OpenCL C
    .language_version:
      - 2
      - 0
    .max_flat_workgroup_size: 512
    .name:           _Z3fwd4Args
    .private_segment_fixed_size: 0
    .sgpr_count:     108
    .sgpr_spill_count: 179
    .symbol:         _Z3fwd4Args.kd
    .uniform_work_group_size: 1
    .uses_dynamic_stack: false
    .vgpr_count:     256
    .vgpr_spill_count: 0
    .wavefront_size: 64
